# adds G9 unit boundary: gather-index loads no longer waited with two vmcnt(0) before the epilogue (deferred to first use), and G1 bias loads issued at K-loop exit
# speedup vs baseline: 1.0060x; 1.0022x over previous
; #define PG8_STAGE(bufoff, gbase, voff) do { _Pragma("unroll") for (int _i = 0; _i < 2; ++_i) \
;         __builtin_amdgcn_global_load_lds((const unsigned*)((const char*)(gbase) + _i * qstep + (voff)), (LAS unsigned*)(lds + (bufoff) + ldsw + _i * 8192), 16, 0, 0); } while (0)
; #define PG8_LDA(dst, b, h) do { _Pragma("unroll") for (int m = 0; m < 4; ++m) _Pragma("unroll") for (int k = 0; k < 2; ++k) dst[m][k] = *(const LAS bf16x8*)(lds + PG8_SA(b, h) + aoff + m * 2048 + k * 1024); } while (0)
; #define PG8_LDB(dst, b, h) do { _Pragma("unroll") for (int n = 0; n < 2; ++n) _Pragma("unroll") for (int k = 0; k < 2; ++k) dst[n][k] = *(const LAS bf16x8*)(lds + PG8_SB(b, h) + boff + n * 2048 + k * 1024); } while (0)
; #define PG8_WAIT_V(n) asm volatile("s_waitcnt vmcnt(" #n ")" ::: "memory")
; #define PG8_WAIT_L(n) asm volatile("s_waitcnt lgkmcnt(" #n ")" ::: "memory")
; #define PG8_BAR __builtin_amdgcn_s_barrier()
; #define PG8_SCHED __builtin_amdgcn_sched_barrier(0)
; template <class Epi, bool GATHER = false>
; __device__ __forceinline__ void gemm_phase(LAS unsigned char* lds, const Gemm g, const Order& S, const Epi& E, const int* gidx = nullptr) {
;     ...
;         for (int t = 0; t < nt; t += 2) {
;             const bool last = (t == nt - 2);
;             if constexpr (Epi::HAS_MID) { if (t == Epi::MID_T) { PG8_SCHED; E.mid(acc, cur, wr, wc, fr, fq); PG8_SCHED; } }
;             const char* a1 = cA + (size_t)(t + 1) * kstep;
;             const char* a2 = last ? nA : cA + (size_t)(t + 2) * kstep; const char* b2 = last ? nB : cB + (size_t)(t + 2) * kstep;
;             const char* a3 = a2 + kstep; const char* b3 = b2 + kstep;
;             PG8_LDB(B0, 0, 0); PG8_LDB(B1, 0, 1); PG8_SCHED; PG8_LDA(At, 0, 0); PG8_STAGE_A(PG8_SA(1, 1), a1, 1, false);
;             PG8_WAIT_V(8); PG8_WAIT_L(0); PG8_BAR; PG8_MMA(0, 0, At, B0); PG8_MMA(0, 1, At, B1); PG8_BAR; PG8_SCHED;
;             PG8_LDA(At, 0, 1); PG8_STAGE(PG8_SB(0, 0), b2, voffB); PG8_STAGE(PG8_SB(0, 1), b2 + hstep, voffB); PG8_STAGE_A(PG8_SA(0, 0), a2, 0, last);
;             PG8_WAIT_V(8); PG8_WAIT_L(0); PG8_BAR; PG8_MMA(1, 0, At, B0); PG8_MMA(1, 1, At, B1); PG8_BAR; PG8_SCHED;
;             PG8_LDB(B0, 1, 0); PG8_LDB(B1, 1, 1); PG8_SCHED; PG8_LDA(At, 1, 0); PG8_STAGE_A(PG8_SA(0, 1), a2, 1, last);
;             PG8_WAIT_V(8); PG8_WAIT_L(0); PG8_BAR; PG8_MMA(0, 0, At, B0); PG8_MMA(0, 1, At, B1); PG8_BAR; PG8_SCHED;
.LBB0_145:
	s_add_u32 s0, s8, 0xfffc0080
	s_addc_u32 s1, s9, -1
	s_add_i32 s37, 0, 0x10000
	s_cmp_eq_u32 s36, 12
	s_cselect_b32 s1, s4, s1
	s_cselect_b32 s0, s5, s0
	s_cselect_b32 vcc_hi, s25, s35
	s_cselect_b32 vcc_lo, s27, s34
	s_add_i32 s50, 0, 0x14000
	v_add_u32_e32 v52, s37, v157
	v_add_u32_e32 v164, s50, v157
	ds_read_b128 v[28:31], v52
	ds_read_b128 v[36:39], v52 offset:1024
	ds_read_b128 v[48:51], v52 offset:2048
	ds_read_b128 v[52:55], v52 offset:3072
	ds_read_b128 v[148:151], v164
	ds_read_b128 v[152:155], v164 offset:1024
	ds_read_b128 v[160:163], v164 offset:2048
	ds_read_b128 v[164:167], v164 offset:3072
	v_lshl_add_u64 v[220:221], s[8:9], 0, v[146:147]
	s_add_i32 m0, s53, 0xc000
	ds_read_b128 v[168:171], v159
	ds_read_b128 v[172:175], v159 offset:1024
	ds_read_b128 v[176:179], v159 offset:2048
	ds_read_b128 v[180:183], v159 offset:3072
	ds_read_b128 v[184:187], v159 offset:4096
	ds_read_b128 v[188:191], v159 offset:5120
	ds_read_b128 v[212:215], v159 offset:6144
	ds_read_b128 v[216:219], v159 offset:7168
	global_load_lds_dwordx4 v[220:221], off
	v_lshl_add_u64 v[220:221], v[220:221], 0, s[90:91]
	s_add_i32 m0, s53, 0xe000
	s_nop 0
	global_load_lds_dwordx4 v[220:221], off
	s_waitcnt vmcnt(8)
	s_waitcnt lgkmcnt(0)
	s_barrier
	s_setprio 3
	s_waitcnt lgkmcnt(0)
	v_mfma_f32_16x16x32_bf16 v[140:143], v[28:31], v[168:171], v[140:143]
	v_mfma_f32_16x16x32_bf16 v[136:139], v[48:51], v[168:171], v[136:139]
	v_mfma_f32_16x16x32_bf16 v[124:127], v[28:31], v[176:179], v[124:127]
	v_mfma_f32_16x16x32_bf16 v[120:123], v[48:51], v[176:179], v[120:123]
	v_mfma_f32_16x16x32_bf16 v[108:111], v[28:31], v[184:187], v[108:111]
	v_mfma_f32_16x16x32_bf16 v[104:107], v[48:51], v[184:187], v[104:107]
	v_mfma_f32_16x16x32_bf16 v[92:95], v[28:31], v[212:215], v[92:95]
	v_mfma_f32_16x16x32_bf16 v[88:91], v[48:51], v[212:215], v[88:91]
	v_mfma_f32_16x16x32_bf16 v[140:143], v[36:39], v[172:175], v[140:143]
	v_mfma_f32_16x16x32_bf16 v[136:139], v[52:55], v[172:175], v[136:139]
	v_mfma_f32_16x16x32_bf16 v[124:127], v[36:39], v[180:183], v[124:127]
	v_mfma_f32_16x16x32_bf16 v[120:123], v[52:55], v[180:183], v[120:123]
	v_mfma_f32_16x16x32_bf16 v[108:111], v[36:39], v[188:191], v[108:111]
	v_mfma_f32_16x16x32_bf16 v[104:107], v[52:55], v[188:191], v[104:107]
	v_mfma_f32_16x16x32_bf16 v[92:95], v[36:39], v[216:219], v[92:95]
	v_mfma_f32_16x16x32_bf16 v[88:91], v[52:55], v[216:219], v[88:91]
	s_setprio 0
	s_setprio 3
	v_mfma_f32_16x16x32_bf16 v[132:135], v[148:151], v[168:171], v[132:135]
	v_mfma_f32_16x16x32_bf16 v[128:131], v[160:163], v[168:171], v[128:131]
	v_mfma_f32_16x16x32_bf16 v[116:119], v[148:151], v[176:179], v[116:119]
	v_mfma_f32_16x16x32_bf16 v[112:115], v[160:163], v[176:179], v[112:115]
	v_mfma_f32_16x16x32_bf16 v[100:103], v[148:151], v[184:187], v[100:103]
	v_mfma_f32_16x16x32_bf16 v[96:99], v[160:163], v[184:187], v[96:99]
	v_mfma_f32_16x16x32_bf16 v[84:87], v[148:151], v[212:215], v[84:87]
	v_mfma_f32_16x16x32_bf16 v[80:83], v[160:163], v[212:215], v[80:83]
	v_mfma_f32_16x16x32_bf16 v[132:135], v[152:155], v[172:175], v[132:135]
	v_mfma_f32_16x16x32_bf16 v[128:131], v[164:167], v[172:175], v[128:131]
	v_mfma_f32_16x16x32_bf16 v[116:119], v[152:155], v[180:183], v[116:119]
	v_mfma_f32_16x16x32_bf16 v[112:115], v[164:167], v[180:183], v[112:115]
	v_mfma_f32_16x16x32_bf16 v[100:103], v[152:155], v[188:191], v[100:103]
	v_mfma_f32_16x16x32_bf16 v[96:99], v[164:167], v[188:191], v[96:99]
	v_mfma_f32_16x16x32_bf16 v[84:87], v[152:155], v[216:219], v[84:87]
	v_mfma_f32_16x16x32_bf16 v[80:83], v[164:167], v[216:219], v[80:83]
	s_setprio 0
	s_barrier
	s_add_i32 s37, s37, s52
	v_lshl_add_u64 v[220:221], vcc, 0, v[194:195]
	s_mov_b32 m0, s37
	ds_read_b128 v[168:171], v159 offset:16384
	ds_read_b128 v[172:175], v159 offset:17408
	ds_read_b128 v[176:179], v159 offset:18432
	ds_read_b128 v[180:183], v159 offset:19456
	ds_read_b128 v[184:187], v159 offset:20480
	ds_read_b128 v[188:191], v159 offset:21504
	ds_read_b128 v[212:215], v159 offset:22528
	ds_read_b128 v[216:219], v159 offset:23552
	global_load_lds_dwordx4 v[220:221], off
	v_lshl_add_u64 v[236:237], v[220:221], 0, s[90:91]
	s_add_i32 m0, s37, 0x2000
	s_add_i32 s37, s50, s52
	global_load_lds_dwordx4 v[236:237], off
	v_lshl_add_u64 v[236:237], v[220:221], 0, s[92:93]
	s_mov_b32 m0, s37
	s_nop 0
	global_load_lds_dwordx4 v[236:237], off
	v_lshl_add_u64 v[236:237], v[220:221], 0, s[94:95]
	s_add_i32 m0, s37, 0x2000
	s_nop 0
	global_load_lds_dwordx4 v[236:237], off
	v_lshl_add_u64 v[236:237], s[0:1], 0, v[144:145]
	s_mov_b32 m0, s53
	v_lshl_add_u64 v[238:239], v[236:237], 0, s[90:91]
	global_load_lds_dwordx4 v[236:237], off
	s_mov_b32 m0, s81
	s_nop 0
	global_load_lds_dwordx4 v[238:239], off
	s_waitcnt vmcnt(8)
	s_waitcnt lgkmcnt(0)
	s_barrier
; #define PG8_STAGE(bufoff, gbase, voff) do { _Pragma("unroll") for (int _i = 0; _i < 2; ++_i) \
;         __builtin_amdgcn_global_load_lds((const unsigned*)((const char*)(gbase) + _i * qstep + (voff)), (LAS unsigned*)(lds + (bufoff) + ldsw + _i * 8192), 16, 0, 0); } while (0)
; #define PG8_LDA(dst, b, h) do { _Pragma("unroll") for (int m = 0; m < 4; ++m) _Pragma("unroll") for (int k = 0; k < 2; ++k) dst[m][k] = *(const LAS bf16x8*)(lds + PG8_SA(b, h) + aoff + m * 2048 + k * 1024); } while (0)
; #define PG8_LDB(dst, b, h) do { _Pragma("unroll") for (int n = 0; n < 2; ++n) _Pragma("unroll") for (int k = 0; k < 2; ++k) dst[n][k] = *(const LAS bf16x8*)(lds + PG8_SB(b, h) + boff + n * 2048 + k * 1024); } while (0)
; #define PG8_MMA(ai, bj, At, Bt) do { __builtin_amdgcn_s_setprio(3); _Pragma("unroll") for (int m = 0; m < 4; ++m) _Pragma("unroll") for (int n = 0; n < 2; ++n) _Pragma("unroll") for (int k = 0; k < 2; ++k) \
;         acc[ai][bj][m][n] = __builtin_amdgcn_mfma_f32_16x16x32_bf16(Bt[n][k], At[m][k], acc[ai][bj][m][n], 0, 0, 0); __builtin_amdgcn_s_setprio(0); } while (0)
; #define PG8_WAIT_V(n) asm volatile("s_waitcnt vmcnt(" #n ")" ::: "memory")
; #define PG8_WAIT_L(n) asm volatile("s_waitcnt lgkmcnt(" #n ")" ::: "memory")
; #define PG8_BAR __builtin_amdgcn_s_barrier()
; #define PG8_SCHED __builtin_amdgcn_sched_barrier(0)
; template <class Epi, bool GATHER = false>
; __device__ __forceinline__ void gemm_phase(LAS unsigned char* lds, const Gemm g, const Order& S, const Epi& E, const int* gidx = nullptr) {
;     ...
;             PG8_WAIT_V(8); PG8_WAIT_L(0); PG8_BAR; PG8_MMA(0, 0, At, B0); PG8_MMA(0, 1, At, B1); PG8_BAR; PG8_SCHED;
;             PG8_LDA(At, 0, 1); PG8_STAGE(PG8_SB(0, 0), b2, voffB); PG8_STAGE(PG8_SB(0, 1), b2 + hstep, voffB); PG8_STAGE_A(PG8_SA(0, 0), a2, 0, last);
;             PG8_WAIT_V(8); PG8_WAIT_L(0); PG8_BAR; PG8_MMA(1, 0, At, B0); PG8_MMA(1, 1, At, B1); PG8_BAR; PG8_SCHED;
;             PG8_LDB(B0, 1, 0); PG8_LDB(B1, 1, 1); PG8_SCHED; PG8_LDA(At, 1, 0); PG8_STAGE_A(PG8_SA(0, 1), a2, 1, last);
;             PG8_WAIT_V(8); PG8_WAIT_L(0); PG8_BAR; PG8_MMA(0, 0, At, B0); PG8_MMA(0, 1, At, B1); PG8_BAR; PG8_SCHED;
	s_setprio 3
	s_waitcnt lgkmcnt(0)
	v_mfma_f32_16x16x32_bf16 v[76:79], v[28:31], v[168:171], v[76:79]
	v_mfma_f32_16x16x32_bf16 v[72:75], v[48:51], v[168:171], v[72:75]
	v_mfma_f32_16x16x32_bf16 v[60:63], v[28:31], v[176:179], v[60:63]
	v_mfma_f32_16x16x32_bf16 v[56:59], v[48:51], v[176:179], v[56:59]
	v_mfma_f32_16x16x32_bf16 v[32:35], v[28:31], v[184:187], v[32:35]
	v_mfma_f32_16x16x32_bf16 v[24:27], v[48:51], v[184:187], v[24:27]
	v_mfma_f32_16x16x32_bf16 v[12:15], v[28:31], v[212:215], v[12:15]
	v_mfma_f32_16x16x32_bf16 v[8:11], v[48:51], v[212:215], v[8:11]
	v_mfma_f32_16x16x32_bf16 v[76:79], v[36:39], v[172:175], v[76:79]
	v_mfma_f32_16x16x32_bf16 v[72:75], v[52:55], v[172:175], v[72:75]
	v_mfma_f32_16x16x32_bf16 v[60:63], v[36:39], v[180:183], v[60:63]
	v_mfma_f32_16x16x32_bf16 v[56:59], v[52:55], v[180:183], v[56:59]
	v_mfma_f32_16x16x32_bf16 v[32:35], v[36:39], v[188:191], v[32:35]
	v_mfma_f32_16x16x32_bf16 v[24:27], v[52:55], v[188:191], v[24:27]
	v_mfma_f32_16x16x32_bf16 v[12:15], v[36:39], v[216:219], v[12:15]
	v_mfma_f32_16x16x32_bf16 v[8:11], v[52:55], v[216:219], v[8:11]
	s_setprio 0
	s_setprio 3
	v_mfma_f32_16x16x32_bf16 v[44:47], v[148:151], v[176:179], v[44:47]
	v_mfma_f32_16x16x32_bf16 v[40:43], v[160:163], v[176:179], v[40:43]
	v_mfma_f32_16x16x32_bf16 v[20:23], v[148:151], v[184:187], v[20:23]
	v_mfma_f32_16x16x32_bf16 v[16:19], v[160:163], v[184:187], v[16:19]
	v_mfma_f32_16x16x32_bf16 v[4:7], v[148:151], v[212:215], v[4:7]
	v_mfma_f32_16x16x32_bf16 v[0:3], v[160:163], v[212:215], v[0:3]
	v_mfma_f32_16x16x32_bf16 v[28:31], v[148:151], v[168:171], v[68:71]
	v_mfma_f32_16x16x32_bf16 v[36:39], v[160:163], v[168:171], v[64:67]
	v_mfma_f32_16x16x32_bf16 v[44:47], v[152:155], v[180:183], v[44:47]
	v_mfma_f32_16x16x32_bf16 v[40:43], v[164:167], v[180:183], v[40:43]
	v_mfma_f32_16x16x32_bf16 v[20:23], v[152:155], v[188:191], v[20:23]
	v_mfma_f32_16x16x32_bf16 v[16:19], v[164:167], v[188:191], v[16:19]
	v_mfma_f32_16x16x32_bf16 v[4:7], v[152:155], v[216:219], v[4:7]
	v_mfma_f32_16x16x32_bf16 v[0:3], v[164:167], v[216:219], v[0:3]
	v_mfma_f32_16x16x32_bf16 v[28:31], v[152:155], v[172:175], v[28:31]
	v_mfma_f32_16x16x32_bf16 v[36:39], v[164:167], v[172:175], v[36:39]
	s_setprio 0
	s_barrier
	s_add_i32 s0, 0, 0x18000
	s_add_i32 s1, 0, 0x1c000
	v_add_u32_e32 v68, s0, v157
	v_add_u32_e32 v164, s1, v157
	ds_read_b128 v[48:51], v68
	ds_read_b128 v[52:55], v68 offset:1024
	ds_read_b128 v[64:67], v68 offset:2048
	ds_read_b128 v[68:71], v68 offset:3072
	ds_read_b128 v[148:151], v164
	ds_read_b128 v[152:155], v164 offset:1024
	ds_read_b128 v[160:163], v164 offset:2048
	ds_read_b128 v[164:167], v164 offset:3072
	s_mov_b32 m0, s82
	v_lshl_add_u64 v[238:239], v[236:237], 0, s[92:93]
	ds_read_b128 v[168:171], v159 offset:32768
	ds_read_b128 v[172:175], v159 offset:33792
	ds_read_b128 v[176:179], v159 offset:34816
	ds_read_b128 v[180:183], v159 offset:35840
	ds_read_b128 v[184:187], v159 offset:36864
	ds_read_b128 v[188:191], v159 offset:37888
	ds_read_b128 v[212:215], v159 offset:38912
	ds_read_b128 v[216:219], v159 offset:39936
	global_load_lds_dwordx4 v[238:239], off
	v_lshl_add_u64 v[238:239], v[236:237], 0, s[94:95]
	s_mov_b32 m0, s83
	s_nop 0
	global_load_lds_dwordx4 v[238:239], off
	s_waitcnt vmcnt(8)
	s_waitcnt lgkmcnt(0)
	s_barrier
	s_setprio 3
	s_waitcnt lgkmcnt(0)
	v_mfma_f32_16x16x32_bf16 v[140:143], v[48:51], v[168:171], v[140:143]
	v_mfma_f32_16x16x32_bf16 v[136:139], v[64:67], v[168:171], v[136:139]
	v_mfma_f32_16x16x32_bf16 v[124:127], v[48:51], v[176:179], v[124:127]
	v_mfma_f32_16x16x32_bf16 v[120:123], v[64:67], v[176:179], v[120:123]
	v_mfma_f32_16x16x32_bf16 v[108:111], v[48:51], v[184:187], v[108:111]
	v_mfma_f32_16x16x32_bf16 v[104:107], v[64:67], v[184:187], v[104:107]
	v_mfma_f32_16x16x32_bf16 v[92:95], v[48:51], v[212:215], v[92:95]
	v_mfma_f32_16x16x32_bf16 v[88:91], v[64:67], v[212:215], v[88:91]
	v_mfma_f32_16x16x32_bf16 v[140:143], v[52:55], v[172:175], v[140:143]
	v_mfma_f32_16x16x32_bf16 v[136:139], v[68:71], v[172:175], v[136:139]
	v_mfma_f32_16x16x32_bf16 v[124:127], v[52:55], v[180:183], v[124:127]
	v_mfma_f32_16x16x32_bf16 v[120:123], v[68:71], v[180:183], v[120:123]
	v_mfma_f32_16x16x32_bf16 v[108:111], v[52:55], v[188:191], v[108:111]
	v_mfma_f32_16x16x32_bf16 v[104:107], v[68:71], v[188:191], v[104:107]
	v_mfma_f32_16x16x32_bf16 v[92:95], v[52:55], v[216:219], v[92:95]
	v_mfma_f32_16x16x32_bf16 v[88:91], v[68:71], v[216:219], v[88:91]
	s_setprio 0
	s_setprio 3
	v_mfma_f32_16x16x32_bf16 v[132:135], v[148:151], v[168:171], v[132:135]
	v_mfma_f32_16x16x32_bf16 v[128:131], v[160:163], v[168:171], v[128:131]
	v_mfma_f32_16x16x32_bf16 v[116:119], v[148:151], v[176:179], v[116:119]
	v_mfma_f32_16x16x32_bf16 v[112:115], v[160:163], v[176:179], v[112:115]
	v_mfma_f32_16x16x32_bf16 v[100:103], v[148:151], v[184:187], v[100:103]
	v_mfma_f32_16x16x32_bf16 v[96:99], v[160:163], v[184:187], v[96:99]
	v_mfma_f32_16x16x32_bf16 v[84:87], v[148:151], v[212:215], v[84:87]
	v_mfma_f32_16x16x32_bf16 v[80:83], v[160:163], v[212:215], v[80:83]
	v_mfma_f32_16x16x32_bf16 v[132:135], v[152:155], v[172:175], v[132:135]
	v_mfma_f32_16x16x32_bf16 v[128:131], v[164:167], v[172:175], v[128:131]
	v_mfma_f32_16x16x32_bf16 v[116:119], v[152:155], v[180:183], v[116:119]
	v_mfma_f32_16x16x32_bf16 v[112:115], v[164:167], v[180:183], v[112:115]
	v_mfma_f32_16x16x32_bf16 v[100:103], v[152:155], v[188:191], v[100:103]
	v_mfma_f32_16x16x32_bf16 v[96:99], v[164:167], v[188:191], v[96:99]
	v_mfma_f32_16x16x32_bf16 v[84:87], v[152:155], v[216:219], v[84:87]
	v_mfma_f32_16x16x32_bf16 v[80:83], v[164:167], v[216:219], v[80:83]
	s_setprio 0
	s_barrier
; #define PG8_STAGE(bufoff, gbase, voff) do { _Pragma("unroll") for (int _i = 0; _i < 2; ++_i) \
;         __builtin_amdgcn_global_load_lds((const unsigned*)((const char*)(gbase) + _i * qstep + (voff)), (LAS unsigned*)(lds + (bufoff) + ldsw + _i * 8192), 16, 0, 0); } while (0)
; #define PG8_LDA(dst, b, h) do { _Pragma("unroll") for (int m = 0; m < 4; ++m) _Pragma("unroll") for (int k = 0; k < 2; ++k) dst[m][k] = *(const LAS bf16x8*)(lds + PG8_SA(b, h) + aoff + m * 2048 + k * 1024); } while (0)
; #define PG8_MMA(ai, bj, At, Bt) do { __builtin_amdgcn_s_setprio(3); _Pragma("unroll") for (int m = 0; m < 4; ++m) _Pragma("unroll") for (int n = 0; n < 2; ++n) _Pragma("unroll") for (int k = 0; k < 2; ++k) \
;         acc[ai][bj][m][n] = __builtin_amdgcn_mfma_f32_16x16x32_bf16(Bt[n][k], At[m][k], acc[ai][bj][m][n], 0, 0, 0); __builtin_amdgcn_s_setprio(0); } while (0)
; #define PG8_WAIT_V(n) asm volatile("s_waitcnt vmcnt(" #n ")" ::: "memory")
; #define PG8_WAIT_L(n) asm volatile("s_waitcnt lgkmcnt(" #n ")" ::: "memory")
; #define PG8_BAR __builtin_amdgcn_s_barrier()
; #define PG8_SCHED __builtin_amdgcn_sched_barrier(0)
; template <class Epi, bool GATHER = false>
; __device__ __forceinline__ void gemm_phase(LAS unsigned char* lds, const Gemm g, const Order& S, const Epi& E, const int* gidx = nullptr) {
;     ...
;             PG8_WAIT_V(8); PG8_WAIT_L(0); PG8_BAR; PG8_MMA(0, 0, At, B0); PG8_MMA(0, 1, At, B1); PG8_BAR; PG8_SCHED;
;             PG8_LDA(At, 1, 1); PG8_STAGE(PG8_SB(1, 0), b3, voffB); PG8_STAGE(PG8_SB(1, 1), b3 + hstep, voffB); PG8_STAGE_A(PG8_SA(1, 0), a3, 0, last);
;             PG8_WAIT_V(8); PG8_WAIT_L(0); PG8_BAR; PG8_MMA(1, 0, At, B0); PG8_MMA(1, 1, At, B1); PG8_BAR; PG8_SCHED;
;         }
;     __device__ __forceinline__ void operator()(const f32x4 (&acc)[2][2][4][2], const Unit& u, int wr, int wc, int fr, int fq) const {
;     ...
;         const int row0 = u.pm * BM + wr * 64 + fr, col0 = colt + wc * 32 + 8 * fq, bcol0 = pn * BM + wc * 32 + 8 * fq;
;         f32x4 bv[2][2];
; #pragma unroll
;         for (int bj = 0; bj < 2; ++bj)
; #pragma unroll
;             for (int n = 0; n < 2; ++n) bv[bj][n] = *(const f32x4*)(bias + bcol0 + bj * HALF + 4 * n);
	s_add_i32 s0, s0, s52
	v_lshl_add_u64 v[238:239], v[220:221], 0, s[96:97]
	s_mov_b32 m0, s0
	ds_read_b128 v[168:171], v159 offset:49152
	ds_read_b128 v[172:175], v159 offset:50176
	ds_read_b128 v[176:179], v159 offset:51200
	ds_read_b128 v[180:183], v159 offset:52224
	ds_read_b128 v[184:187], v159 offset:53248
	ds_read_b128 v[188:191], v159 offset:54272
	ds_read_b128 v[212:215], v159 offset:55296
	ds_read_b128 v[216:219], v159 offset:56320
	global_load_lds_dwordx4 v[238:239], off
	v_lshl_add_u64 v[238:239], v[220:221], 0, s[58:59]
	s_add_i32 m0, s0, 0x2000
	s_add_i32 s0, s1, s52
	global_load_lds_dwordx4 v[238:239], off
	v_lshl_add_u64 v[238:239], v[220:221], 0, s[62:63]
	s_mov_b32 m0, s0
	v_lshl_add_u64 v[220:221], v[220:221], 0, s[64:65]
	global_load_lds_dwordx4 v[238:239], off
	s_add_i32 m0, s0, 0x2000
	s_nop 0
	global_load_lds_dwordx4 v[220:221], off
	v_lshl_add_u64 v[220:221], v[236:237], 0, s[96:97]
	s_mov_b32 m0, s84
	s_nop 0
	global_load_lds_dwordx4 v[220:221], off
	v_lshl_add_u64 v[220:221], v[236:237], 0, s[58:59]
	s_mov_b32 m0, s85
	s_nop 0
	global_load_lds_dwordx4 v[220:221], off
	s_waitcnt vmcnt(8)
	s_waitcnt lgkmcnt(0)
	s_barrier
	s_setprio 3
	s_waitcnt lgkmcnt(0)
	v_mfma_f32_16x16x32_bf16 v[76:79], v[48:51], v[168:171], v[76:79]
	v_mfma_f32_16x16x32_bf16 v[72:75], v[64:67], v[168:171], v[72:75]
	v_mfma_f32_16x16x32_bf16 v[60:63], v[48:51], v[176:179], v[60:63]
	v_mfma_f32_16x16x32_bf16 v[56:59], v[64:67], v[176:179], v[56:59]
	v_mfma_f32_16x16x32_bf16 v[32:35], v[48:51], v[184:187], v[32:35]
	v_mfma_f32_16x16x32_bf16 v[24:27], v[64:67], v[184:187], v[24:27]
	v_mfma_f32_16x16x32_bf16 v[12:15], v[48:51], v[212:215], v[12:15]
	v_mfma_f32_16x16x32_bf16 v[8:11], v[64:67], v[212:215], v[8:11]
	v_mfma_f32_16x16x32_bf16 v[76:79], v[52:55], v[172:175], v[76:79]
	v_mfma_f32_16x16x32_bf16 v[72:75], v[68:71], v[172:175], v[72:75]
	v_mfma_f32_16x16x32_bf16 v[60:63], v[52:55], v[180:183], v[60:63]
	v_mfma_f32_16x16x32_bf16 v[56:59], v[68:71], v[180:183], v[56:59]
	v_mfma_f32_16x16x32_bf16 v[32:35], v[52:55], v[188:191], v[32:35]
	v_mfma_f32_16x16x32_bf16 v[24:27], v[68:71], v[188:191], v[24:27]
	v_mfma_f32_16x16x32_bf16 v[12:15], v[52:55], v[216:219], v[12:15]
	v_mfma_f32_16x16x32_bf16 v[8:11], v[68:71], v[216:219], v[8:11]
	s_setprio 0
	s_setprio 3
	v_mfma_f32_16x16x32_bf16 v[28:31], v[148:151], v[168:171], v[28:31]
	v_mfma_f32_16x16x32_bf16 v[68:71], v[152:155], v[172:175], v[28:31]
	v_mfma_f32_16x16x32_bf16 v[28:31], v[160:163], v[168:171], v[36:39]
	v_mfma_f32_16x16x32_bf16 v[64:67], v[164:167], v[172:175], v[28:31]
	v_mfma_f32_16x16x32_bf16 v[28:31], v[148:151], v[176:179], v[44:47]
	v_mfma_f32_16x16x32_bf16 v[44:47], v[152:155], v[180:183], v[28:31]
	v_mfma_f32_16x16x32_bf16 v[28:31], v[160:163], v[176:179], v[40:43]
	v_mfma_f32_16x16x32_bf16 v[20:23], v[148:151], v[184:187], v[20:23]
	v_mfma_f32_16x16x32_bf16 v[16:19], v[160:163], v[184:187], v[16:19]
	v_mfma_f32_16x16x32_bf16 v[4:7], v[148:151], v[212:215], v[4:7]
	v_mfma_f32_16x16x32_bf16 v[0:3], v[160:163], v[212:215], v[0:3]
	v_mfma_f32_16x16x32_bf16 v[40:43], v[164:167], v[180:183], v[28:31]
	v_mfma_f32_16x16x32_bf16 v[20:23], v[152:155], v[188:191], v[20:23]
	v_mfma_f32_16x16x32_bf16 v[16:19], v[164:167], v[188:191], v[16:19]
	v_mfma_f32_16x16x32_bf16 v[4:7], v[152:155], v[216:219], v[4:7]
	v_mfma_f32_16x16x32_bf16 v[0:3], v[164:167], v[216:219], v[0:3]
	s_setprio 0
	s_barrier
	s_add_i32 s36, s36, 2
	s_add_u32 s8, s8, 0x100
	s_addc_u32 s9, s9, 0
	s_add_u32 s34, s34, 0x100
	s_addc_u32 s35, s35, 0
	s_cmp_gt_u32 s36, 13
	s_cbranch_scc0 .LBB0_145
	s_lshl_b32 s27, s88, 8
	v_or_b32_e32 v28, s27, v158
	v_ashrrev_i32_e32 v29, 31, v28
	v_lshl_add_u64 v[36:37], v[28:29], 2, s[20:21]
	global_load_dwordx4 v[52:55], v[36:37], off
	global_load_dwordx4 v[48:51], v[36:37], off offset:16
	global_load_dwordx4 v[28:31], v[36:37], off offset:528
	s_nop 0
	global_load_dwordx4 v[36:39], v[36:37], off offset:512
	s_and_b64 vcc, exec, s[22:23]
	s_cbranch_vccz .LBB0_148
	s_barrier

; __device__ __forceinline__ f32x2 sigmoid_pk(f32x2 x) { const f32x2 t = x * (-1.44269504089f); f32x2 e; e.x = __builtin_amdgcn_exp2f(t.x); e.y = __builtin_amdgcn_exp2f(t.y); const f32x2 d = e + 1.0f; f32x2 r; r.x = __builtin_amdgcn_rcpf(d.x); r.y = __builtin_amdgcn_rcpf(d.y); return r; }
; __device__ __forceinline__ f32x2 gelu_tanh_pk(f32x2 x) { const f32x2 x2 = x * x; const f32x2 z = x * (x2 * (1.5957691216057308f * 0.044715f) + 1.5957691216057308f); return x * sigmoid_pk(z); }
;     __device__ __forceinline__ void operator()(const f32x4 (&acc)[2][2][4][2], const Unit& u, int wr, int wc, int fr, int fq) const {
;     ...
;                 for (int bj = 0; bj < 2; ++bj) { f32x4 v0 = acc[ai][bj][m][0] + bv[bj][0], v1 = acc[ai][bj][m][1] + bv[bj][1];
;                     if (act == 1) { const f32x2 a = gelu_tanh_pk((f32x2){v0[0], v0[1]}), b = gelu_tanh_pk((f32x2){v0[2], v0[3]}), c = gelu_tanh_pk((f32x2){v1[0], v1[1]}), d = gelu_tanh_pk((f32x2){v1[2], v1[3]});
;                         v0 = (f32x4){a.x, a.y, b.x, b.y}; v1 = (f32x4){c.x, c.y, d.x, d.y}; }
;                     else if (act == 2) { const f32x2 a = sigmoid_pk((f32x2){v0[0], v0[1]}), b = sigmoid_pk((f32x2){v0[2], v0[3]}), c = sigmoid_pk((f32x2){v1[0], v1[1]}), d = sigmoid_pk((f32x2){v1[2], v1[3]});
.LBB0_159:
	s_xor_b64 s[4:5], s[4:5], -1
	s_mov_b64 s[8:9], -1
	s_and_b64 vcc, exec, s[4:5]
	s_waitcnt vmcnt(0)
	v_pk_add_f32 v[142:143], v[142:143], v[54:55]
	v_pk_add_f32 v[140:141], v[140:141], v[52:53]
	v_pk_add_f32 v[138:139], v[138:139], v[50:51]
	v_pk_add_f32 v[136:137], v[136:137], v[48:49]
	s_cbranch_vccz .LBB0_162
	s_andn2_b64 vcc, exec, s[34:35]
	s_cbranch_vccnz .LBB0_242
	v_pk_mul_f32 v[148:149], v[140:141], s[44:45] op_sel_hi:[1,0]
	v_pk_mul_f32 v[150:151], v[142:143], s[44:45] op_sel_hi:[1,0]
	v_exp_f32_e32 v148, v148
	v_exp_f32_e32 v149, v149
	v_exp_f32_e32 v152, v150
	v_exp_f32_e32 v153, v151
	v_pk_mul_f32 v[154:155], v[138:139], s[44:45] op_sel_hi:[1,0]
	v_pk_add_f32 v[148:149], v[148:149], 1.0 op_sel_hi:[1,0]
	v_exp_f32_e32 v160, v154
	v_rcp_f32_e32 v150, v148
	v_rcp_f32_e32 v151, v149
	v_pk_add_f32 v[148:149], v[152:153], 1.0 op_sel_hi:[1,0]
	v_pk_mul_f32 v[152:153], v[136:137], s[44:45] op_sel_hi:[1,0]
	v_exp_f32_e32 v161, v155
	v_exp_f32_e32 v152, v152
	v_exp_f32_e32 v153, v153
	v_rcp_f32_e32 v148, v148
	v_rcp_f32_e32 v149, v149
	s_mov_b64 s[8:9], 0
	v_pk_add_f32 v[152:153], v[152:153], 1.0 op_sel_hi:[1,0]
	s_nop 0
	v_rcp_f32_e32 v154, v152
	v_rcp_f32_e32 v155, v153
	v_pk_add_f32 v[152:153], v[160:161], 1.0 op_sel_hi:[1,0]
	s_nop 0
	v_rcp_f32_e32 v152, v152
	v_rcp_f32_e32 v153, v153

; template <class Epi, bool GATHER = false>
; __device__ __forceinline__ void gemm_phase(LAS unsigned char* lds, const Gemm g, const Order& S, const Epi& E, const int* gidx = nullptr) {
;     ...
;         if constexpr (GATHER) {
; #pragma unroll
;             for (int q = 0; q < 4; ++q) { gc[q] = gn[q]; if (has2) gn[q] = (unsigned)t4[q] * (unsigned)(K * 2) + (unsigned)C2; } }
; #pragma unroll
;         for (int a = 0; a < 2; ++a)
; #pragma unroll
;             for (int b = 0; b < 2; ++b)
; #pragma unroll
;                 for (int m = 0; m < 4; ++m)
; #pragma unroll
;                     for (int n = 0; n < 2; ++n) acc[a][b][m][n] = (f32x4){0.f, 0.f, 0.f, 0.f};
;         cur = nxt; cA = nA; cB = nB; ++ui;
.LBB0_765:
	s_waitcnt vmcnt(8)
	v_lshlrev_b32_e32 v129, 11, v129
	v_lshlrev_b32_e32 v131, 11, v131
	v_lshlrev_b32_e32 v150, 11, v150
	v_lshlrev_b32_e32 v151, 11, v151
	v_add_u32_e32 v0, v129, v139
	v_cndmask_b32_e64 v1, v140, v0, s[0:1]
	v_add_u32_e32 v0, v131, v139
	v_cndmask_b32_e64 v2, v142, v0, s[0:1]
	v_add_u32_e32 v0, v150, v139
	v_cndmask_b32_e64 v3, v144, v0, s[0:1]
	v_add_u32_e32 v0, v151, v139
	v_cndmask_b32_e64 v4, v145, v0, s[0:1]
	v_mov_b32_e32 v0, 0
	v_mov_b32_e32 v141, v140
	v_mov_b32_e32 v143, v142
	v_mov_b32_e32 v128, v144
	v_mov_b32_e32 v130, v145
	v_mov_b32_e32 v140, v1
	v_mov_b32_e32 v142, v2
	v_mov_b32_e32 v144, v3
	v_mov_b32_e32 v145, v4
	s_mov_b32 s53, s41
	s_mov_b32 s81, s26
	v_mov_b32_e32 v1, v0
	v_mov_b32_e32 v2, v0
	v_mov_b32_e32 v3, v0
	v_mov_b32_e32 v4, v0
	v_mov_b32_e32 v5, v0
	v_mov_b32_e32 v6, v0
	v_mov_b32_e32 v7, v0
	v_mov_b32_e32 v8, v0
	v_mov_b32_e32 v9, v0
	v_mov_b32_e32 v10, v0
	v_mov_b32_e32 v11, v0
	v_mov_b32_e32 v12, v0
	v_mov_b32_e32 v13, v0
	v_mov_b32_e32 v14, v0
	v_mov_b32_e32 v15, v0
	v_mov_b32_e32 v16, v0
	v_mov_b32_e32 v17, v0
	v_mov_b32_e32 v18, v0
	v_mov_b32_e32 v19, v0
	v_mov_b32_e32 v20, v0
	v_mov_b32_e32 v21, v0
	v_mov_b32_e32 v22, v0
	v_mov_b32_e32 v23, v0
	v_mov_b32_e32 v24, v0
	v_mov_b32_e32 v25, v0
	v_mov_b32_e32 v26, v0
	v_mov_b32_e32 v27, v0
	v_mov_b32_e32 v28, v0
	v_mov_b32_e32 v29, v0
	v_mov_b32_e32 v30, v0
	v_mov_b32_e32 v31, v0
	v_mov_b32_e32 v32, v0
	v_mov_b32_e32 v33, v0
	v_mov_b32_e32 v34, v0
	v_mov_b32_e32 v35, v0
	v_mov_b32_e32 v36, v0
	v_mov_b32_e32 v37, v0
	v_mov_b32_e32 v38, v0
	v_mov_b32_e32 v39, v0
	v_mov_b32_e32 v40, v0
	v_mov_b32_e32 v41, v0
	v_mov_b32_e32 v42, v0
	v_mov_b32_e32 v43, v0
	v_mov_b32_e32 v44, v0
	v_mov_b32_e32 v45, v0
	v_mov_b32_e32 v46, v0
	v_mov_b32_e32 v47, v0
	v_mov_b32_e32 v48, v0
	v_mov_b32_e32 v49, v0
	v_mov_b32_e32 v50, v0
	v_mov_b32_e32 v51, v0
	v_mov_b32_e32 v52, v0
	v_mov_b32_e32 v53, v0
	v_mov_b32_e32 v54, v0
	v_mov_b32_e32 v55, v0
	v_mov_b32_e32 v56, v0
	v_mov_b32_e32 v57, v0
	v_mov_b32_e32 v58, v0
	v_mov_b32_e32 v59, v0
	v_mov_b32_e32 v60, v0
	v_mov_b32_e32 v61, v0
	v_mov_b32_e32 v62, v0
	v_mov_b32_e32 v63, v0
	v_mov_b32_e32 v64, v0
	v_mov_b32_e32 v65, v0
	v_mov_b32_e32 v66, v0
	v_mov_b32_e32 v67, v0
	v_mov_b32_e32 v68, v0
	v_mov_b32_e32 v69, v0
	v_mov_b32_e32 v70, v0
	v_mov_b32_e32 v71, v0
	v_mov_b32_e32 v72, v0
	v_mov_b32_e32 v73, v0
	v_mov_b32_e32 v74, v0
	v_mov_b32_e32 v75, v0
	v_mov_b32_e32 v76, v0
	v_mov_b32_e32 v77, v0
	v_mov_b32_e32 v78, v0
	v_mov_b32_e32 v79, v0
	v_mov_b32_e32 v80, v0
	v_mov_b32_e32 v81, v0
	v_mov_b32_e32 v82, v0
	v_mov_b32_e32 v83, v0
	v_mov_b32_e32 v84, v0
	v_mov_b32_e32 v85, v0
	v_mov_b32_e32 v86, v0
	v_mov_b32_e32 v87, v0
	v_mov_b32_e32 v88, v0
	v_mov_b32_e32 v89, v0
	v_mov_b32_e32 v90, v0
	v_mov_b32_e32 v91, v0
	v_mov_b32_e32 v92, v0
	v_mov_b32_e32 v93, v0
	v_mov_b32_e32 v94, v0
	v_mov_b32_e32 v95, v0
	v_mov_b32_e32 v96, v0
	v_mov_b32_e32 v97, v0
	v_mov_b32_e32 v98, v0
	v_mov_b32_e32 v99, v0
	v_mov_b32_e32 v100, v0
	v_mov_b32_e32 v101, v0
	v_mov_b32_e32 v102, v0
	v_mov_b32_e32 v103, v0
	v_mov_b32_e32 v104, v0
	v_mov_b32_e32 v105, v0
	v_mov_b32_e32 v106, v0
	v_mov_b32_e32 v107, v0
	v_mov_b32_e32 v108, v0
	v_mov_b32_e32 v109, v0
	v_mov_b32_e32 v110, v0
	v_mov_b32_e32 v111, v0
	v_mov_b32_e32 v112, v0
	v_mov_b32_e32 v113, v0
	v_mov_b32_e32 v114, v0
	v_mov_b32_e32 v115, v0
	v_mov_b32_e32 v116, v0
	v_mov_b32_e32 v117, v0
	v_mov_b32_e32 v118, v0
	v_mov_b32_e32 v119, v0
	v_mov_b32_e32 v120, v0
	v_mov_b32_e32 v121, v0
	v_mov_b32_e32 v122, v0
	v_mov_b32_e32 v123, v0
	v_mov_b32_e32 v124, v0
	v_mov_b32_e32 v125, v0
	v_mov_b32_e32 v126, v0
	v_mov_b32_e32 v127, v0
	s_mov_b32 s82, s83
	s_andn2_b64 vcc, exec, s[6:7]
	s_mov_b64 s[0:1], s[28:29]
	s_cbranch_vccz .LBB0_781

; template <class Epi, bool GATHER = false>
; __device__ __forceinline__ void gemm_phase(LAS unsigned char* lds, const Gemm g, const Order& S, const Epi& E, const int* gidx = nullptr) {
;     ...
;         int t4[4] = {0, 0, 0, 0}; bool has2 = false;
;         if constexpr (GATHER) { Unit u2; has2 = has_next && S.next(ui + 2, u2);
;             if (has2) {
; #pragma unroll
;                 for (int q = 0; q < 4; ++q) t4[q] = gidx[u2.pm * BM + q * 64 + Rl]; } }
.LBB0_775:
	v_mov_b32_e32 v129, 0
	s_andn2_b64 vcc, exec, s[0:1]
	v_mov_b32_e32 v131, 0
	v_mov_b32_e32 v150, 0
	v_mov_b32_e32 v151, 0
	s_cbranch_vccnz .LBB0_777
	v_lshl_add_u32 v134, s52, 8, v138
	v_ashrrev_i32_e32 v135, 31, v134
	v_lshl_add_u64 v[136:137], v[134:135], 2, s[14:15]
	global_load_dword v129, v[136:137], off
	v_add_u32_e32 v136, 64, v134
	v_ashrrev_i32_e32 v137, 31, v136
	v_lshl_add_u64 v[136:137], v[136:137], 2, s[14:15]
	global_load_dword v131, v[136:137], off
	v_add_u32_e32 v136, 0x80, v134
	v_add_u32_e32 v134, 0xc0, v134
	v_ashrrev_i32_e32 v137, 31, v136
	v_ashrrev_i32_e32 v135, 31, v134
	v_lshl_add_u64 v[136:137], v[136:137], 2, s[14:15]
	v_lshl_add_u64 v[134:135], v[134:135], 2, s[14:15]
	global_load_dword v150, v[136:137], off
	global_load_dword v151, v[134:135], off
